# leftover 16 tiles of the N=1024 GEMMs split into 64x64 pieces over all workgroups: split-K over waves, 128B-line K mapping, LDS reduce, same bf16 MFMA/f32 acc
# speedup vs baseline: 1.0084x; 1.0084x over previous
; #define STAGE_A(P, BASE, br, kt) STAGE_B(P, BASE, br, kt)
; template <int EPI, int N, int K>
; __device__ __forceinline__ void gemm_phase(const KP& p, int l, const bfr* A, const bfr* Bt) {
;     ...
;   constexpr int TM = 256, HM = 128;
;   const int nM = T_ROWS / TM, nN = N / BM, nwg = nM * nN;
;   int tid = threadIdx.x; asm volatile("" : "+v"(tid));
;   const int wid = tid >> 6, lane = tid & 63, wr = wid >> 2, wc = wid & 3, fr = lane & 15, fq = lane >> 4;
;   const int nt = K / BK;
;   unsigned so0, so1;
;   { int _r, _c; stage_rc(tid * 16, _r, _c); so0 = (unsigned)(_r * K + _c) * 2u; stage_rc(tid * 16 + 8192, _r, _c); so1 = (unsigned)(_r * K + _c) * 2u; }
;     ...
;   int brow = 0, bcol = 0, pn = 0;
;   if (p.bid < nwg) {
;     TILE_COORDS(p.bid, brow, bcol, pn);
;     STAGE_B(SB(0, 0), Bt, bcol, 0); STAGE_A(SA(0, 0), A, brow, 0);
;     STAGE_B(SB(0, 1), Bt, bcol + HALF, 0); STAGE_A(SA(0, 1), A, brow + HM, 0);
;   }
;   for (int Lt = p.bid; Lt < nwg; Lt += p.nblk) {
;     f32x4 acc[2][2][4][2];
; #pragma unroll
;     for (int a = 0; a < 2; ++a)
; #pragma unroll
;       for (int b = 0; b < 2; ++b)
; #pragma unroll
;         for (int m = 0; m < 4; ++m)
; #pragma unroll
;           for (int n = 0; n < 2; ++n) acc[a][b][m][n] = f32x4{0.f, 0.f, 0.f, 0.f};
.LBB0_34:
	s_mov_b32 s98, 0x904904
	s_lshr_b32 s98, s98, s68
	s_and_b32 s98, s98, 1
	s_cbranch_scc0 .Lsub_skip
	s_mov_b64 exec, -1
	v_writelane_b32 v174, s4, 0
	v_writelane_b32 v174, s5, 1
	v_writelane_b32 v174, s6, 2
	v_writelane_b32 v174, s7, 3
	v_writelane_b32 v174, s8, 4
	v_writelane_b32 v174, s9, 5
	v_writelane_b32 v174, s10, 6
	v_writelane_b32 v174, s11, 7
	v_writelane_b32 v174, s12, 8
	v_writelane_b32 v174, s13, 9
	v_writelane_b32 v174, s14, 10
	v_writelane_b32 v174, s15, 11
	v_writelane_b32 v174, s16, 12
	v_writelane_b32 v174, s17, 13
	v_writelane_b32 v174, s18, 14
	v_writelane_b32 v174, s19, 15
	v_writelane_b32 v174, s20, 16
	v_writelane_b32 v174, s21, 17
	v_writelane_b32 v174, s22, 18
	v_writelane_b32 v174, s23, 19
	v_writelane_b32 v174, s24, 20
	v_writelane_b32 v174, s25, 21
	v_writelane_b32 v174, s26, 22
	v_writelane_b32 v174, s27, 23
	s_waitcnt vmcnt(0) lgkmcnt(0)
	s_barrier
	v_readlane_b32 s20, v255, 45
	v_readlane_b32 s21, v255, 46
	v_readlane_b32 s12, v255, 42
	s_cmp_ge_u32 s68, 13
	s_cselect_b32 s17, 1, 0
	s_mul_i32 s18, s17, 12
	s_sub_i32 s25, s68, s18
	s_add_i32 s25, s25, -1
	s_movk_i32 s11, 0x1600
	s_mov_b32 s9, 6
	s_mov_b32 s10, 1
	s_mov_b32 s18, 0x4329000
	s_mov_b32 s19, 0xb00000
	s_cmp_eq_u32 s25, 10
	s_cselect_b32 s19, 0x2500000, s19
	s_cmp_eq_u32 s25, 7
	s_cselect_b32 s19, 0x1800000, s19
	s_cselect_b32 s18, 0x12a29000, s18
	s_cselect_b32 s11, 0x800, s11
	s_cselect_b32 s9, 2, s9
	s_cselect_b32 s10, 0, s10
	s_mul_i32 s22, s17, 0x2a80000
	s_add_u32 s22, s22, 0x16c29000
	s_add_u32 s22, s22, s19
	s_add_u32 s6, s20, s22
	s_addc_u32 s7, s21, 0
	s_add_u32 s4, s20, s18
	s_addc_u32 s5, s21, 0
	s_and_b32 s13, s12, 15
	s_lshr_b32 s14, s12, 4
	s_and_b32 s15, s13, 7
	s_mul_i32 s15, s15, 0x42
	s_lshr_b32 s16, s13, 3
	s_add_i32 s15, s15, s16
	s_add_i32 s15, s15, 64
	s_lshr_b32 s16, s15, 5
	s_and_b32 s15, s15, 31
	s_cmp_eq_u32 s16, 16
	s_cbranch_scc1 .Lsub_lastgrp
	s_lshl_b32 s16, s16, 3
	s_and_b32 s23, s15, 7
	s_add_i32 s16, s16, s23
	s_lshr_b32 s15, s15, 3
	s_branch .Lsub_havepm
.Lsub_lastgrp:
	s_and_b32 s23, s15, 3
	s_add_i32 s16, s23, 0x80
	s_lshr_b32 s15, s15, 2
.Lsub_havepm:
	s_lshl_b32 s16, s16, 8
	s_lshl_b32 s15, s15, 8
	s_lshr_b32 s23, s14, 2
	s_lshl_b32 s23, s23, 6
	s_add_i32 s16, s16, s23
	s_and_b32 s23, s14, 3
	s_lshl_b32 s23, s23, 6
	s_add_i32 s15, s15, s23
	v_lshrrev_b32_e32 v248, 6, v156
	s_nop 1
	v_readfirstlane_b32 s24, v248
	s_nop 3
	s_cmp_eq_u32 s10, 1
	s_cbranch_scc1 .Lsub_k2816
	s_lshl_b32 s23, s24, 8
	s_branch .Lsub_khave
.Lsub_k2816:
	s_mul_i32 s23, s24, 6
	s_cmp_lt_u32 s24, 4
	s_cbranch_scc1 .Lsub_klo
	s_mul_i32 s23, s24, 5
	s_add_i32 s23, s23, 4
	s_mov_b32 s9, 5
.Lsub_klo:
	s_lshl_b32 s23, s23, 7
.Lsub_khave:
	s_mul_i32 s26, s16, s11
	s_mul_hi_u32 s27, s16, s11
	s_add_u32 s4, s4, s26
	s_addc_u32 s5, s5, s27
	s_add_u32 s4, s4, s23
	s_addc_u32 s5, s5, 0
	s_mul_i32 s26, s15, s11
	s_mul_hi_u32 s27, s15, s11
	s_add_u32 s6, s6, s26
	s_addc_u32 s7, s7, s27
	s_add_u32 s6, s6, s23
	s_addc_u32 s7, s7, 0
	v_and_b32_e32 v248, 15, v156
	v_bfe_u32 v249, v156, 4, 2
	v_mul_lo_u32 v240, v248, s11
	v_lshl_add_u32 v240, v249, 5, v240
	s_lshl_b32 s26, s11, 4
	v_add_u32_e32 v241, s26, v240
	v_add_u32_e32 v242, s26, v241
	v_add_u32_e32 v243, s26, v242
	global_load_dwordx4 v[68:71], v240, s[4:5]
	global_load_dwordx4 v[72:75], v240, s[4:5] offset:16
	global_load_dwordx4 v[76:79], v241, s[4:5]
	global_load_dwordx4 v[80:83], v241, s[4:5] offset:16
	global_load_dwordx4 v[84:87], v242, s[4:5]
	global_load_dwordx4 v[88:91], v242, s[4:5] offset:16
	global_load_dwordx4 v[92:95], v243, s[4:5]
	global_load_dwordx4 v[96:99], v243, s[4:5] offset:16
	global_load_dwordx4 v[100:103], v240, s[6:7]
	global_load_dwordx4 v[104:107], v240, s[6:7] offset:16
	global_load_dwordx4 v[108:111], v241, s[6:7]
	global_load_dwordx4 v[112:115], v241, s[6:7] offset:16
	global_load_dwordx4 v[116:119], v242, s[6:7]
	global_load_dwordx4 v[120:123], v242, s[6:7] offset:16
	global_load_dwordx4 v[124:127], v243, s[6:7]
	global_load_dwordx4 v[128:131], v243, s[6:7] offset:16
	s_add_u32 s4, s4, 0x80
	s_addc_u32 s5, s5, 0
	s_add_u32 s6, s6, 0x80
	s_addc_u32 s7, s7, 0
	global_load_dwordx4 v[176:179], v240, s[4:5]
	global_load_dwordx4 v[180:183], v240, s[4:5] offset:16
	global_load_dwordx4 v[184:187], v241, s[4:5]
	global_load_dwordx4 v[188:191], v241, s[4:5] offset:16
	global_load_dwordx4 v[192:195], v242, s[4:5]
	global_load_dwordx4 v[196:199], v242, s[4:5] offset:16
	global_load_dwordx4 v[200:203], v243, s[4:5]
	global_load_dwordx4 v[204:207], v243, s[4:5] offset:16
	global_load_dwordx4 v[208:211], v240, s[6:7]
	global_load_dwordx4 v[212:215], v240, s[6:7] offset:16
	global_load_dwordx4 v[216:219], v241, s[6:7]
	global_load_dwordx4 v[220:223], v241, s[6:7] offset:16
	global_load_dwordx4 v[224:227], v242, s[6:7]
	global_load_dwordx4 v[228:231], v242, s[6:7] offset:16
	global_load_dwordx4 v[232:235], v243, s[6:7]
	global_load_dwordx4 v[236:239], v243, s[6:7] offset:16
	s_add_u32 s4, s4, 0x80
	s_addc_u32 s5, s5, 0
	s_add_u32 s6, s6, 0x80
	s_addc_u32 s7, s7, 0
	v_mov_b32_e32 v4, 0
	v_mov_b32_e32 v5, 0
	v_mov_b32_e32 v6, 0
	v_mov_b32_e32 v7, 0
	v_mov_b32_e32 v8, 0
	v_mov_b32_e32 v9, 0
	v_mov_b32_e32 v10, 0
	v_mov_b32_e32 v11, 0
	v_mov_b32_e32 v12, 0
	v_mov_b32_e32 v13, 0
	v_mov_b32_e32 v14, 0
	v_mov_b32_e32 v15, 0
	v_mov_b32_e32 v16, 0
	v_mov_b32_e32 v17, 0
	v_mov_b32_e32 v18, 0
	v_mov_b32_e32 v19, 0
	v_mov_b32_e32 v20, 0
	v_mov_b32_e32 v21, 0
	v_mov_b32_e32 v22, 0
	v_mov_b32_e32 v23, 0
	v_mov_b32_e32 v24, 0
	v_mov_b32_e32 v25, 0
	v_mov_b32_e32 v26, 0
	v_mov_b32_e32 v27, 0
	v_mov_b32_e32 v28, 0
	v_mov_b32_e32 v29, 0
	v_mov_b32_e32 v30, 0
	v_mov_b32_e32 v31, 0
	v_mov_b32_e32 v32, 0
	v_mov_b32_e32 v33, 0
	v_mov_b32_e32 v34, 0
	v_mov_b32_e32 v35, 0
	v_mov_b32_e32 v36, 0
	v_mov_b32_e32 v37, 0
	v_mov_b32_e32 v38, 0
	v_mov_b32_e32 v39, 0
	v_mov_b32_e32 v40, 0
	v_mov_b32_e32 v41, 0
	v_mov_b32_e32 v42, 0
	v_mov_b32_e32 v43, 0
	v_mov_b32_e32 v44, 0
	v_mov_b32_e32 v45, 0
	v_mov_b32_e32 v46, 0
	v_mov_b32_e32 v47, 0
	v_mov_b32_e32 v48, 0
	v_mov_b32_e32 v49, 0
	v_mov_b32_e32 v50, 0
	v_mov_b32_e32 v51, 0
	v_mov_b32_e32 v52, 0
	v_mov_b32_e32 v53, 0
	v_mov_b32_e32 v54, 0
	v_mov_b32_e32 v55, 0
	v_mov_b32_e32 v56, 0
	v_mov_b32_e32 v57, 0
	v_mov_b32_e32 v58, 0
	v_mov_b32_e32 v59, 0
	v_mov_b32_e32 v60, 0
	v_mov_b32_e32 v61, 0
	v_mov_b32_e32 v62, 0
	v_mov_b32_e32 v63, 0
	v_mov_b32_e32 v64, 0
	v_mov_b32_e32 v65, 0
	v_mov_b32_e32 v66, 0
	v_mov_b32_e32 v67, 0
	s_mov_b32 s8, 0
; #define STAGE_A(P, BASE, br, kt) STAGE_B(P, BASE, br, kt)
; #define LDA(dst, b, h) for (int m = 0; m < 4; ++m) for (int k = 0; k < 2; ++k) \
;     dst[m][k] = *reinterpret_cast<const bf16x8*>((char*)SA(b, h) + lds_byte(wr * 64 + m * 16 + fr, k * 32 + fq * 8))
; #define LDB(dst, b, h) for (int n = 0; n < 2; ++n) for (int k = 0; k < 2; ++k) \
;     dst[n][k] = *reinterpret_cast<const bf16x8*>((char*)SB(b, h) + lds_byte(wc * 32 + n * 16 + fr, k * 32 + fq * 8))
; #define MMA(ai, bj, At, Bq) do { __builtin_amdgcn_s_setprio(1); \
;     for (int m = 0; m < 4; ++m) for (int n = 0; n < 2; ++n) for (int k = 0; k < 2; ++k) \
;       acc[ai][bj][m][n] = __builtin_amdgcn_mfma_f32_16x16x32_bf16(Bq[n][k], At[m][k], acc[ai][bj][m][n], 0, 0, 0); \
;     __builtin_amdgcn_s_setprio(0); } while (0)
; #define WAIT_V(n) asm volatile("s_waitcnt vmcnt(" #n ")" ::: "memory")
; #define WAIT_L(n) asm volatile("s_waitcnt lgkmcnt(" #n ")" ::: "memory")
; #define BAR __builtin_amdgcn_s_barrier()
; #define SCHED __builtin_amdgcn_sched_barrier(0)
; template <int EPI, int N, int K>
; __device__ __forceinline__ void gemm_phase(const KP& p, int l, const bfr* A, const bfr* Bt) {
;     ...
;     for (int t = 0; t < nt - 2; t += 2) {
;       LDB(B0, 0, 0); SCHED; LDA(At, 0, 0); STAGE_A(SA(1, 1), A, brow + HM, t + 1);
;       WAIT_L(8); BAR; WAIT_L(0); MMA(0, 0, At, B0); BAR; SCHED;
;       LDB(B1, 0, 1); STAGE_B(SB(0, 0), Bt, bcol, t + 2);
;       BAR; WAIT_L(0); MMA(0, 1, At, B1); BAR;
;       LDA(At, 0, 1); STAGE_A(SA(0, 0), A, brow, t + 2);
;       BAR; WAIT_L(0); MMA(1, 0, At, B0); BAR; SCHED;
;       STAGE_B(SB(0, 1), Bt, bcol + HALF, t + 2);
;       WAIT_V(6); BAR; MMA(1, 1, At, B1); BAR;
;       LDB(B0, 1, 0); SCHED; LDA(At, 1, 0); STAGE_A(SA(0, 1), A, brow + HM, t + 2);
;       WAIT_L(8); BAR; WAIT_L(0); MMA(0, 0, At, B0); BAR; SCHED;
;       LDB(B1, 1, 1); STAGE_B(SB(1, 0), Bt, bcol, t + 3);
;       BAR; WAIT_L(0); MMA(0, 1, At, B1); BAR;
;       LDA(At, 1, 1); STAGE_A(SA(1, 0), A, brow, t + 3);
;       BAR; WAIT_L(0); MMA(1, 0, At, B0); BAR; SCHED;
;       STAGE_B(SB(1, 1), Bt, bcol + HALF, t + 3);
;       WAIT_V(6); BAR; MMA(1, 1, At, B1); BAR;
;     }
.Lsub_loop:
	s_sub_i32 s17, s9, s8
	s_cmp_eq_u32 s17, 1
	s_cbranch_scc1 .Lsub_one
	s_waitcnt vmcnt(16)
	v_mfma_f32_16x16x32_bf16 v[4:7], v[100:103], v[68:71], v[4:7]
	v_mfma_f32_16x16x32_bf16 v[8:11], v[100:103], v[76:79], v[8:11]
	v_mfma_f32_16x16x32_bf16 v[12:15], v[100:103], v[84:87], v[12:15]
	v_mfma_f32_16x16x32_bf16 v[16:19], v[100:103], v[92:95], v[16:19]
	v_mfma_f32_16x16x32_bf16 v[20:23], v[108:111], v[68:71], v[20:23]
	v_mfma_f32_16x16x32_bf16 v[24:27], v[108:111], v[76:79], v[24:27]
	v_mfma_f32_16x16x32_bf16 v[28:31], v[108:111], v[84:87], v[28:31]
	v_mfma_f32_16x16x32_bf16 v[32:35], v[108:111], v[92:95], v[32:35]
	v_mfma_f32_16x16x32_bf16 v[36:39], v[116:119], v[68:71], v[36:39]
	v_mfma_f32_16x16x32_bf16 v[40:43], v[116:119], v[76:79], v[40:43]
	v_mfma_f32_16x16x32_bf16 v[44:47], v[116:119], v[84:87], v[44:47]
	v_mfma_f32_16x16x32_bf16 v[48:51], v[116:119], v[92:95], v[48:51]
	v_mfma_f32_16x16x32_bf16 v[52:55], v[124:127], v[68:71], v[52:55]
	v_mfma_f32_16x16x32_bf16 v[56:59], v[124:127], v[76:79], v[56:59]
	v_mfma_f32_16x16x32_bf16 v[60:63], v[124:127], v[84:87], v[60:63]
	v_mfma_f32_16x16x32_bf16 v[64:67], v[124:127], v[92:95], v[64:67]
	v_mfma_f32_16x16x32_bf16 v[4:7], v[104:107], v[72:75], v[4:7]
	v_mfma_f32_16x16x32_bf16 v[8:11], v[104:107], v[80:83], v[8:11]
	v_mfma_f32_16x16x32_bf16 v[12:15], v[104:107], v[88:91], v[12:15]
	v_mfma_f32_16x16x32_bf16 v[16:19], v[104:107], v[96:99], v[16:19]
	v_mfma_f32_16x16x32_bf16 v[20:23], v[112:115], v[72:75], v[20:23]
	v_mfma_f32_16x16x32_bf16 v[24:27], v[112:115], v[80:83], v[24:27]
	v_mfma_f32_16x16x32_bf16 v[28:31], v[112:115], v[88:91], v[28:31]
	v_mfma_f32_16x16x32_bf16 v[32:35], v[112:115], v[96:99], v[32:35]
	v_mfma_f32_16x16x32_bf16 v[36:39], v[120:123], v[72:75], v[36:39]
	v_mfma_f32_16x16x32_bf16 v[40:43], v[120:123], v[80:83], v[40:43]
	v_mfma_f32_16x16x32_bf16 v[44:47], v[120:123], v[88:91], v[44:47]
	v_mfma_f32_16x16x32_bf16 v[48:51], v[120:123], v[96:99], v[48:51]
	v_mfma_f32_16x16x32_bf16 v[52:55], v[128:131], v[72:75], v[52:55]
	v_mfma_f32_16x16x32_bf16 v[56:59], v[128:131], v[80:83], v[56:59]
	v_mfma_f32_16x16x32_bf16 v[60:63], v[128:131], v[88:91], v[60:63]
	v_mfma_f32_16x16x32_bf16 v[64:67], v[128:131], v[96:99], v[64:67]
	s_cmp_eq_u32 s17, 2
	s_cbranch_scc1 .Lsub_two
	global_load_dwordx4 v[68:71], v240, s[4:5]
	global_load_dwordx4 v[72:75], v240, s[4:5] offset:16
	global_load_dwordx4 v[76:79], v241, s[4:5]
	global_load_dwordx4 v[80:83], v241, s[4:5] offset:16
	global_load_dwordx4 v[84:87], v242, s[4:5]
	global_load_dwordx4 v[88:91], v242, s[4:5] offset:16
	global_load_dwordx4 v[92:95], v243, s[4:5]
	global_load_dwordx4 v[96:99], v243, s[4:5] offset:16
	global_load_dwordx4 v[100:103], v240, s[6:7]
	global_load_dwordx4 v[104:107], v240, s[6:7] offset:16
	global_load_dwordx4 v[108:111], v241, s[6:7]
	global_load_dwordx4 v[112:115], v241, s[6:7] offset:16
	global_load_dwordx4 v[116:119], v242, s[6:7]
	global_load_dwordx4 v[120:123], v242, s[6:7] offset:16
	global_load_dwordx4 v[124:127], v243, s[6:7]
	global_load_dwordx4 v[128:131], v243, s[6:7] offset:16
	s_add_u32 s4, s4, 0x80
	s_addc_u32 s5, s5, 0
	s_add_u32 s6, s6, 0x80
	s_addc_u32 s7, s7, 0
	s_waitcnt vmcnt(16)
	v_mfma_f32_16x16x32_bf16 v[4:7], v[208:211], v[176:179], v[4:7]
	v_mfma_f32_16x16x32_bf16 v[8:11], v[208:211], v[184:187], v[8:11]
	v_mfma_f32_16x16x32_bf16 v[12:15], v[208:211], v[192:195], v[12:15]
	v_mfma_f32_16x16x32_bf16 v[16:19], v[208:211], v[200:203], v[16:19]
	v_mfma_f32_16x16x32_bf16 v[20:23], v[216:219], v[176:179], v[20:23]
	v_mfma_f32_16x16x32_bf16 v[24:27], v[216:219], v[184:187], v[24:27]
	v_mfma_f32_16x16x32_bf16 v[28:31], v[216:219], v[192:195], v[28:31]
	v_mfma_f32_16x16x32_bf16 v[32:35], v[216:219], v[200:203], v[32:35]
	v_mfma_f32_16x16x32_bf16 v[36:39], v[224:227], v[176:179], v[36:39]
	v_mfma_f32_16x16x32_bf16 v[40:43], v[224:227], v[184:187], v[40:43]
	v_mfma_f32_16x16x32_bf16 v[44:47], v[224:227], v[192:195], v[44:47]
	v_mfma_f32_16x16x32_bf16 v[48:51], v[224:227], v[200:203], v[48:51]
	v_mfma_f32_16x16x32_bf16 v[52:55], v[232:235], v[176:179], v[52:55]
	v_mfma_f32_16x16x32_bf16 v[56:59], v[232:235], v[184:187], v[56:59]
	v_mfma_f32_16x16x32_bf16 v[60:63], v[232:235], v[192:195], v[60:63]
	v_mfma_f32_16x16x32_bf16 v[64:67], v[232:235], v[200:203], v[64:67]
	v_mfma_f32_16x16x32_bf16 v[4:7], v[212:215], v[180:183], v[4:7]
	v_mfma_f32_16x16x32_bf16 v[8:11], v[212:215], v[188:191], v[8:11]
	v_mfma_f32_16x16x32_bf16 v[12:15], v[212:215], v[196:199], v[12:15]
	v_mfma_f32_16x16x32_bf16 v[16:19], v[212:215], v[204:207], v[16:19]
	v_mfma_f32_16x16x32_bf16 v[20:23], v[220:223], v[180:183], v[20:23]
	v_mfma_f32_16x16x32_bf16 v[24:27], v[220:223], v[188:191], v[24:27]
	v_mfma_f32_16x16x32_bf16 v[28:31], v[220:223], v[196:199], v[28:31]
	v_mfma_f32_16x16x32_bf16 v[32:35], v[220:223], v[204:207], v[32:35]
	v_mfma_f32_16x16x32_bf16 v[36:39], v[228:231], v[180:183], v[36:39]
	v_mfma_f32_16x16x32_bf16 v[40:43], v[228:231], v[188:191], v[40:43]
	v_mfma_f32_16x16x32_bf16 v[44:47], v[228:231], v[196:199], v[44:47]
	v_mfma_f32_16x16x32_bf16 v[48:51], v[228:231], v[204:207], v[48:51]
	v_mfma_f32_16x16x32_bf16 v[52:55], v[236:239], v[180:183], v[52:55]
	v_mfma_f32_16x16x32_bf16 v[56:59], v[236:239], v[188:191], v[56:59]
	v_mfma_f32_16x16x32_bf16 v[60:63], v[236:239], v[196:199], v[60:63]
	v_mfma_f32_16x16x32_bf16 v[64:67], v[236:239], v[204:207], v[64:67]
	s_add_i32 s8, s8, 2
	s_cmp_eq_u32 s17, 3
	s_cbranch_scc1 .Lsub_loop
	global_load_dwordx4 v[176:179], v240, s[4:5]
	global_load_dwordx4 v[180:183], v240, s[4:5] offset:16
	global_load_dwordx4 v[184:187], v241, s[4:5]
	global_load_dwordx4 v[188:191], v241, s[4:5] offset:16
	global_load_dwordx4 v[192:195], v242, s[4:5]
	global_load_dwordx4 v[196:199], v242, s[4:5] offset:16
	global_load_dwordx4 v[200:203], v243, s[4:5]
	global_load_dwordx4 v[204:207], v243, s[4:5] offset:16
	global_load_dwordx4 v[208:211], v240, s[6:7]
	global_load_dwordx4 v[212:215], v240, s[6:7] offset:16
	global_load_dwordx4 v[216:219], v241, s[6:7]
	global_load_dwordx4 v[220:223], v241, s[6:7] offset:16
	global_load_dwordx4 v[224:227], v242, s[6:7]
	global_load_dwordx4 v[228:231], v242, s[6:7] offset:16
	global_load_dwordx4 v[232:235], v243, s[6:7]
	global_load_dwordx4 v[236:239], v243, s[6:7] offset:16
	s_add_u32 s4, s4, 0x80
	s_addc_u32 s5, s5, 0
	s_add_u32 s6, s6, 0x80
	s_addc_u32 s7, s7, 0
	s_branch .Lsub_loop
; #define STAGE_A(P, BASE, br, kt) STAGE_B(P, BASE, br, kt)
; #define LDA(dst, b, h) for (int m = 0; m < 4; ++m) for (int k = 0; k < 2; ++k) \
;     dst[m][k] = *reinterpret_cast<const bf16x8*>((char*)SA(b, h) + lds_byte(wr * 64 + m * 16 + fr, k * 32 + fq * 8))
; #define LDB(dst, b, h) for (int n = 0; n < 2; ++n) for (int k = 0; k < 2; ++k) \
;     dst[n][k] = *reinterpret_cast<const bf16x8*>((char*)SB(b, h) + lds_byte(wc * 32 + n * 16 + fr, k * 32 + fq * 8))
; #define MMA(ai, bj, At, Bq) do { __builtin_amdgcn_s_setprio(1); \
;     for (int m = 0; m < 4; ++m) for (int n = 0; n < 2; ++n) for (int k = 0; k < 2; ++k) \
;       acc[ai][bj][m][n] = __builtin_amdgcn_mfma_f32_16x16x32_bf16(Bq[n][k], At[m][k], acc[ai][bj][m][n], 0, 0, 0); \
;     __builtin_amdgcn_s_setprio(0); } while (0)
; #define WAIT_V(n) asm volatile("s_waitcnt vmcnt(" #n ")" ::: "memory")
; #define WAIT_L(n) asm volatile("s_waitcnt lgkmcnt(" #n ")" ::: "memory")
; #define BAR __builtin_amdgcn_s_barrier()
; template <int EPI, int N, int K>
; __device__ __forceinline__ void gemm_phase(const KP& p, int l, const bfr* A, const bfr* Bt) {
;     ...
;     { LDB(B0, 0, 0); LDA(At, 0, 0); STAGE_A(SA(1, 1), A, brow + HM, nt - 1);
;       BAR; WAIT_L(0); MMA(0, 0, At, B0); BAR;
;       LDB(B1, 0, 1); BAR; WAIT_L(0); MMA(0, 1, At, B1); BAR;
;       LDA(At, 0, 1); WAIT_V(4); BAR; WAIT_L(0); MMA(1, 0, At, B0); MMA(1, 1, At, B1); BAR; }
;     { LDB(B0, 1, 0); LDA(At, 1, 0); WAIT_V(2); BAR; WAIT_L(0); MMA(0, 0, At, B0); BAR;
;       LDB(B1, 1, 1); WAIT_V(0); BAR; WAIT_L(0); MMA(0, 1, At, B1); BAR;
;       LDA(At, 1, 1); BAR; WAIT_L(0); MMA(1, 0, At, B0); MMA(1, 1, At, B1); BAR; }
.Lsub_two:
	s_waitcnt vmcnt(0)
	v_mfma_f32_16x16x32_bf16 v[4:7], v[208:211], v[176:179], v[4:7]
	v_mfma_f32_16x16x32_bf16 v[8:11], v[208:211], v[184:187], v[8:11]
	v_mfma_f32_16x16x32_bf16 v[12:15], v[208:211], v[192:195], v[12:15]
	v_mfma_f32_16x16x32_bf16 v[16:19], v[208:211], v[200:203], v[16:19]
	v_mfma_f32_16x16x32_bf16 v[20:23], v[216:219], v[176:179], v[20:23]
	v_mfma_f32_16x16x32_bf16 v[24:27], v[216:219], v[184:187], v[24:27]
	v_mfma_f32_16x16x32_bf16 v[28:31], v[216:219], v[192:195], v[28:31]
	v_mfma_f32_16x16x32_bf16 v[32:35], v[216:219], v[200:203], v[32:35]
	v_mfma_f32_16x16x32_bf16 v[36:39], v[224:227], v[176:179], v[36:39]
	v_mfma_f32_16x16x32_bf16 v[40:43], v[224:227], v[184:187], v[40:43]
	v_mfma_f32_16x16x32_bf16 v[44:47], v[224:227], v[192:195], v[44:47]
	v_mfma_f32_16x16x32_bf16 v[48:51], v[224:227], v[200:203], v[48:51]
	v_mfma_f32_16x16x32_bf16 v[52:55], v[232:235], v[176:179], v[52:55]
	v_mfma_f32_16x16x32_bf16 v[56:59], v[232:235], v[184:187], v[56:59]
	v_mfma_f32_16x16x32_bf16 v[60:63], v[232:235], v[192:195], v[60:63]
	v_mfma_f32_16x16x32_bf16 v[64:67], v[232:235], v[200:203], v[64:67]
	v_mfma_f32_16x16x32_bf16 v[4:7], v[212:215], v[180:183], v[4:7]
	v_mfma_f32_16x16x32_bf16 v[8:11], v[212:215], v[188:191], v[8:11]
	v_mfma_f32_16x16x32_bf16 v[12:15], v[212:215], v[196:199], v[12:15]
	v_mfma_f32_16x16x32_bf16 v[16:19], v[212:215], v[204:207], v[16:19]
	v_mfma_f32_16x16x32_bf16 v[20:23], v[220:223], v[180:183], v[20:23]
	v_mfma_f32_16x16x32_bf16 v[24:27], v[220:223], v[188:191], v[24:27]
	v_mfma_f32_16x16x32_bf16 v[28:31], v[220:223], v[196:199], v[28:31]
	v_mfma_f32_16x16x32_bf16 v[32:35], v[220:223], v[204:207], v[32:35]
	v_mfma_f32_16x16x32_bf16 v[36:39], v[228:231], v[180:183], v[36:39]
	v_mfma_f32_16x16x32_bf16 v[40:43], v[228:231], v[188:191], v[40:43]
	v_mfma_f32_16x16x32_bf16 v[44:47], v[228:231], v[196:199], v[44:47]
	v_mfma_f32_16x16x32_bf16 v[48:51], v[228:231], v[204:207], v[48:51]
	v_mfma_f32_16x16x32_bf16 v[52:55], v[236:239], v[180:183], v[52:55]
	v_mfma_f32_16x16x32_bf16 v[56:59], v[236:239], v[188:191], v[56:59]
	v_mfma_f32_16x16x32_bf16 v[60:63], v[236:239], v[196:199], v[60:63]
	v_mfma_f32_16x16x32_bf16 v[64:67], v[236:239], v[204:207], v[64:67]
	s_branch .Lsub_kdone
.Lsub_one:
	s_waitcnt vmcnt(0)
	v_mfma_f32_16x16x32_bf16 v[4:7], v[100:103], v[68:71], v[4:7]
	v_mfma_f32_16x16x32_bf16 v[8:11], v[100:103], v[76:79], v[8:11]
	v_mfma_f32_16x16x32_bf16 v[12:15], v[100:103], v[84:87], v[12:15]
	v_mfma_f32_16x16x32_bf16 v[16:19], v[100:103], v[92:95], v[16:19]
	v_mfma_f32_16x16x32_bf16 v[20:23], v[108:111], v[68:71], v[20:23]
	v_mfma_f32_16x16x32_bf16 v[24:27], v[108:111], v[76:79], v[24:27]
	v_mfma_f32_16x16x32_bf16 v[28:31], v[108:111], v[84:87], v[28:31]
	v_mfma_f32_16x16x32_bf16 v[32:35], v[108:111], v[92:95], v[32:35]
	v_mfma_f32_16x16x32_bf16 v[36:39], v[116:119], v[68:71], v[36:39]
	v_mfma_f32_16x16x32_bf16 v[40:43], v[116:119], v[76:79], v[40:43]
	v_mfma_f32_16x16x32_bf16 v[44:47], v[116:119], v[84:87], v[44:47]
	v_mfma_f32_16x16x32_bf16 v[48:51], v[116:119], v[92:95], v[48:51]
	v_mfma_f32_16x16x32_bf16 v[52:55], v[124:127], v[68:71], v[52:55]
	v_mfma_f32_16x16x32_bf16 v[56:59], v[124:127], v[76:79], v[56:59]
	v_mfma_f32_16x16x32_bf16 v[60:63], v[124:127], v[84:87], v[60:63]
	v_mfma_f32_16x16x32_bf16 v[64:67], v[124:127], v[92:95], v[64:67]
	v_mfma_f32_16x16x32_bf16 v[4:7], v[104:107], v[72:75], v[4:7]
	v_mfma_f32_16x16x32_bf16 v[8:11], v[104:107], v[80:83], v[8:11]
	v_mfma_f32_16x16x32_bf16 v[12:15], v[104:107], v[88:91], v[12:15]
	v_mfma_f32_16x16x32_bf16 v[16:19], v[104:107], v[96:99], v[16:19]
	v_mfma_f32_16x16x32_bf16 v[20:23], v[112:115], v[72:75], v[20:23]
	v_mfma_f32_16x16x32_bf16 v[24:27], v[112:115], v[80:83], v[24:27]
	v_mfma_f32_16x16x32_bf16 v[28:31], v[112:115], v[88:91], v[28:31]
	v_mfma_f32_16x16x32_bf16 v[32:35], v[112:115], v[96:99], v[32:35]
	v_mfma_f32_16x16x32_bf16 v[36:39], v[120:123], v[72:75], v[36:39]
	v_mfma_f32_16x16x32_bf16 v[40:43], v[120:123], v[80:83], v[40:43]
	v_mfma_f32_16x16x32_bf16 v[44:47], v[120:123], v[88:91], v[44:47]
	v_mfma_f32_16x16x32_bf16 v[48:51], v[120:123], v[96:99], v[48:51]
	v_mfma_f32_16x16x32_bf16 v[52:55], v[128:131], v[72:75], v[52:55]
	v_mfma_f32_16x16x32_bf16 v[56:59], v[128:131], v[80:83], v[56:59]
	v_mfma_f32_16x16x32_bf16 v[60:63], v[128:131], v[88:91], v[60:63]
	v_mfma_f32_16x16x32_bf16 v[64:67], v[128:131], v[96:99], v[64:67]
; __device__ __forceinline__ unsigned pack2(float a, float b) { f32v2_t v = {a, b}; bf16v2_t r = __builtin_convertvector(v, bf16v2_t); return __builtin_bit_cast(unsigned, r); }
; template <int EPI, int N, int K>
; __device__ __forceinline__ void gemm_phase(const KP& p, int l, const bfr* A, const bfr* Bt) {
;     ...
;     } else if (EPI == 2) {
;       bfr* hb = (bfr*)(p.ws + OFF_HB);
; #pragma unroll
;       for (int ai = 0; ai < 2; ++ai)
; #pragma unroll
;         for (int m = 0; m < 4; ++m) {
;           int row = erow + ai * HM + wr * 64 + m * 16 + fr;
; #pragma unroll
;           for (int bj = 0; bj < 2; ++bj) {
;             u32x4* hp = (u32x4*)(hb + (size_t)row * DM + ecol + bj * HALF + wc * 32 + fq * 8);
;             u32x4 h = *hp, o;
; #pragma unroll
;             for (int q2 = 0; q2 < 4; ++q2) {
;               f32v2_t hv2 = {__uint_as_float(h[q2] << 16), __uint_as_float(h[q2] & 0xffff0000u)};
;               f32v2_t av2 = {acc[ai][bj][m][q2 >> 1][(q2 & 1) * 2], acc[ai][bj][m][q2 >> 1][(q2 & 1) * 2 + 1]};
;               f32v2_t s2 = hv2 + av2;
;               o[q2] = pack2(s2.x, s2.y);
;             }
;             *hp = o;
;           }
;         }
.Lsub_kdone:
	s_nop 7
	s_nop 7
	v_and_b32_e32 v248, 63, v156
	v_lshlrev_b32_e32 v248, 4, v248
	s_lshl_b32 s17, s24, 14
	v_add_u32_e32 v249, s17, v248
	ds_write_b128 v249, v[4:7]
	ds_write_b128 v249, v[8:11] offset:1024
	ds_write_b128 v249, v[12:15] offset:2048
	ds_write_b128 v249, v[16:19] offset:3072
	ds_write_b128 v249, v[20:23] offset:4096
	ds_write_b128 v249, v[24:27] offset:5120
	ds_write_b128 v249, v[28:31] offset:6144
	ds_write_b128 v249, v[32:35] offset:7168
	ds_write_b128 v249, v[36:39] offset:8192
	ds_write_b128 v249, v[40:43] offset:9216
	ds_write_b128 v249, v[44:47] offset:10240
	ds_write_b128 v249, v[48:51] offset:11264
	ds_write_b128 v249, v[52:55] offset:12288
	ds_write_b128 v249, v[56:59] offset:13312
	ds_write_b128 v249, v[60:63] offset:14336
	ds_write_b128 v249, v[64:67] offset:15360
	s_waitcnt lgkmcnt(0)
	s_barrier
	s_lshr_b32 s17, s24, 2
	s_lshl_b32 s17, s17, 3
	s_and_b32 s18, s24, 3
	s_add_i32 s17, s17, s18
	s_lshl_b32 s17, s17, 10
	v_add_u32_e32 v250, s17, v248
	v_add_u32_e32 v251, 0x10000, v250
	ds_read_b128 v[68:71], v250
	ds_read_b128 v[72:75], v250 offset:16384
	ds_read_b128 v[76:79], v250 offset:32768
	ds_read_b128 v[80:83], v250 offset:49152
	ds_read_b128 v[84:87], v251
	ds_read_b128 v[88:91], v251 offset:16384
	ds_read_b128 v[92:95], v251 offset:32768
	ds_read_b128 v[96:99], v251 offset:49152
	ds_read_b128 v[100:103], v250 offset:4096
	ds_read_b128 v[104:107], v250 offset:20480
	ds_read_b128 v[108:111], v250 offset:36864
	ds_read_b128 v[112:115], v250 offset:53248
	ds_read_b128 v[116:119], v251 offset:4096
	ds_read_b128 v[120:123], v251 offset:20480
	ds_read_b128 v[124:127], v251 offset:36864
	ds_read_b128 v[128:131], v251 offset:53248
	s_and_b32 s18, s24, 3
	s_lshl_b32 s18, s18, 4
	s_add_i32 s18, s18, s16
	v_and_b32_e32 v252, 15, v156
	v_add_u32_e32 v252, s18, v252
	v_lshlrev_b32_e32 v252, 11, v252
	s_lshr_b32 s17, s24, 2
	s_lshl_b32 s17, s17, 5
	s_add_i32 s17, s17, s15
	v_bfe_u32 v253, v156, 4, 2
	v_lshl_add_u32 v253, v253, 3, s17
	v_lshl_add_u32 v252, v253, 1, v252
	global_load_dwordx4 v[132:135], v252, s[20:21]
	s_waitcnt lgkmcnt(0)
	v_add_f32_e32 v68, v68, v72
	v_add_f32_e32 v100, v100, v104
	v_add_f32_e32 v69, v69, v73
	v_add_f32_e32 v101, v101, v105
	v_add_f32_e32 v70, v70, v74
	v_add_f32_e32 v102, v102, v106
	v_add_f32_e32 v71, v71, v75
	v_add_f32_e32 v103, v103, v107
	v_add_f32_e32 v68, v68, v76
	v_add_f32_e32 v100, v100, v108
	v_add_f32_e32 v69, v69, v77
	v_add_f32_e32 v101, v101, v109
	v_add_f32_e32 v70, v70, v78
	v_add_f32_e32 v102, v102, v110
	v_add_f32_e32 v71, v71, v79
	v_add_f32_e32 v103, v103, v111
	v_add_f32_e32 v68, v68, v80
	v_add_f32_e32 v100, v100, v112
	v_add_f32_e32 v69, v69, v81
	v_add_f32_e32 v101, v101, v113
	v_add_f32_e32 v70, v70, v82
	v_add_f32_e32 v102, v102, v114
	v_add_f32_e32 v71, v71, v83
	v_add_f32_e32 v103, v103, v115
	v_add_f32_e32 v68, v68, v84
	v_add_f32_e32 v100, v100, v116
	v_add_f32_e32 v69, v69, v85
	v_add_f32_e32 v101, v101, v117
	v_add_f32_e32 v70, v70, v86
	v_add_f32_e32 v102, v102, v118
	v_add_f32_e32 v71, v71, v87
	v_add_f32_e32 v103, v103, v119
	v_add_f32_e32 v68, v68, v88
	v_add_f32_e32 v100, v100, v120
	v_add_f32_e32 v69, v69, v89
	v_add_f32_e32 v101, v101, v121
	v_add_f32_e32 v70, v70, v90
	v_add_f32_e32 v102, v102, v122
	v_add_f32_e32 v71, v71, v91
	v_add_f32_e32 v103, v103, v123
	v_add_f32_e32 v68, v68, v92
	v_add_f32_e32 v100, v100, v124
	v_add_f32_e32 v69, v69, v93
	v_add_f32_e32 v101, v101, v125
	v_add_f32_e32 v70, v70, v94
	v_add_f32_e32 v102, v102, v126
	v_add_f32_e32 v71, v71, v95
	v_add_f32_e32 v103, v103, v127
	v_add_f32_e32 v68, v68, v96
	v_add_f32_e32 v100, v100, v128
	v_add_f32_e32 v69, v69, v97
	v_add_f32_e32 v101, v101, v129
	v_add_f32_e32 v70, v70, v98
	v_add_f32_e32 v102, v102, v130
	v_add_f32_e32 v71, v71, v99
	v_add_f32_e32 v103, v103, v131
	s_waitcnt vmcnt(0)
	v_lshlrev_b32_e32 v248, 16, v132
	v_and_b32_e32 v249, 0xffff0000, v132
	v_add_f32_e32 v248, v248, v68
	v_add_f32_e32 v249, v249, v69
	v_cvt_pk_bf16_f32 v136, v248, v249
	v_lshlrev_b32_e32 v248, 16, v133
	v_and_b32_e32 v249, 0xffff0000, v133
	v_add_f32_e32 v248, v248, v70
	v_add_f32_e32 v249, v249, v71
	v_cvt_pk_bf16_f32 v137, v248, v249
	v_lshlrev_b32_e32 v248, 16, v134
	v_and_b32_e32 v249, 0xffff0000, v134
	v_add_f32_e32 v248, v248, v100
	v_add_f32_e32 v249, v249, v101
	v_cvt_pk_bf16_f32 v138, v248, v249
	v_lshlrev_b32_e32 v248, 16, v135
	v_and_b32_e32 v249, 0xffff0000, v135
	v_add_f32_e32 v248, v248, v102
	v_add_f32_e32 v249, v249, v103
	v_cvt_pk_bf16_f32 v139, v248, v249
	global_store_dwordx4 v252, v[136:139], s[20:21]
	s_waitcnt lgkmcnt(0)
	s_barrier
	v_readlane_b32 s4, v174, 0
	v_readlane_b32 s5, v174, 1
	v_readlane_b32 s6, v174, 2
	v_readlane_b32 s7, v174, 3
	v_readlane_b32 s8, v174, 4
	v_readlane_b32 s9, v174, 5
	v_readlane_b32 s10, v174, 6
	v_readlane_b32 s11, v174, 7
	v_readlane_b32 s12, v174, 8
	v_readlane_b32 s13, v174, 9
	v_readlane_b32 s14, v174, 10
	v_readlane_b32 s15, v174, 11
	v_readlane_b32 s16, v174, 12
	v_readlane_b32 s17, v174, 13
	v_readlane_b32 s18, v174, 14
	v_readlane_b32 s19, v174, 15
	v_readlane_b32 s20, v174, 16
	v_readlane_b32 s21, v174, 17
	v_readlane_b32 s22, v174, 18
	v_readlane_b32 s23, v174, 19
	v_readlane_b32 s24, v174, 20
	v_readlane_b32 s25, v174, 21
	v_readlane_b32 s26, v174, 22
	v_readlane_b32 s27, v174, 23
	s_nop 3

; #define STAGE_A(P, BASE, br, kt) STAGE_B(P, BASE, br, kt)
; template <int EPI, int N, int K>
; __device__ __forceinline__ void gemm_phase(const KP& p, int l, const bfr* A, const bfr* Bt) {
;     ...
;   if (p.bid < nwg) {
;     TILE_COORDS(p.bid, brow, bcol, pn);
;     STAGE_B(SB(0, 0), Bt, bcol, 0); STAGE_A(SA(0, 0), A, brow, 0);
;     STAGE_B(SB(0, 1), Bt, bcol + HALF, 0); STAGE_A(SA(0, 1), A, brow + HM, 0);
;   }
; __device__ void run_phase(const KP& p_, int ph) {
;     ...
;     else if (q == 7) { gemm_phase<2, DM, DM>(p, l, mix, Wl + W_OUT); if (l == 0) { plo = 5440; phi = 6140; } }
.LBB0_294:
	v_readlane_b32 s0, v255, 61
	s_cmp_eq_u32 s0, 7
	s_cbranch_scc0 .LBB0_306
	v_readlane_b32 s0, v255, 42
	v_mov_b32_e32 v0, v156
	s_cmpk_gt_i32 s0, 0x1ff
	v_readlane_b32 s40, v255, 41
	s_cbranch_scc1 .LBB0_307
	s_waitcnt vmcnt(0)
	v_bfe_i32 v3, v0, 27, 1
	v_lshlrev_b32_e32 v136, 4, v0
	v_lshrrev_b32_e32 v3, 22, v3
	v_add_u32_e32 v3, v136, v3
	v_and_b32_e32 v3, 0xfffffc00, v3
	v_sub_u32_e32 v3, v136, v3
	v_lshrrev_b32_e32 v4, 4, v3
	v_bitop3_b32 v3, v4, v3, 32 bitop3:0x6c
	v_ashrrev_i32_e32 v2, 31, v0
	v_ashrrev_i32_e32 v5, 31, v3
	v_lshrrev_b32_e32 v2, 26, v2
	v_lshrrev_b32_e32 v5, 26, v5
	v_add_u32_e32 v2, v0, v2
	v_add_u32_e32 v5, v3, v5
	v_readlane_b32 s0, v255, 57
	v_ashrrev_i32_e32 v2, 6, v2
	v_lshrrev_b32_e32 v6, 6, v5
	v_and_b32_e32 v5, 0xc0, v5
	s_add_u32 s33, s0, 0x1800000
	v_readlane_b32 s0, v255, 58
	v_lshlrev_b32_e32 v4, 3, v2
	v_lshlrev_b32_e32 v2, 5, v2
	v_sub_u32_e32 v3, v3, v5
	v_readlane_b32 s80, v255, 42
	s_addc_u32 s72, s0, 0
	v_and_b32_e32 v4, 0x1ffff0, v4
	v_and_b32_e32 v2, 32, v2
	v_ashrrev_i16_sdwa v3, v163, sext(v3) dst_sel:DWORD dst_unused:UNUSED_PAD src0_sel:DWORD src1_sel:BYTE_0
	s_ashr_i32 s0, s80, 31
	v_add_u32_sdwa v2, v2, sext(v3) dst_sel:DWORD dst_unused:UNUSED_PAD src0_sel:DWORD src1_sel:WORD_0
	v_add_lshl_u32 v3, v6, v4, 11
	s_lshr_b32 s0, s0, 29
	v_lshl_add_u32 v137, v2, 1, v3
	v_add_u32_e32 v2, 0x2000, v136
	s_add_i32 s0, s80, s0
	v_ashrrev_i32_e32 v3, 31, v2
	s_ashr_i32 s1, s0, 3
	s_and_b32 s0, s0, -8
	v_lshrrev_b32_e32 v3, 22, v3
	s_sub_i32 s0, s80, s0
	v_add_u32_e32 v3, v2, v3
	s_cmp_lt_i32 s0, 0
	s_movk_i32 s2, 0x43
	v_ashrrev_i32_e32 v3, 10, v3
	s_cselect_b32 s2, s2, 0x42
	v_mul_i32_i24_e32 v4, 0x400, v3
	s_mul_i32 s0, s2, s0
	v_sub_u32_e32 v2, v2, v4
	s_add_i32 s0, s0, s1
	v_lshrrev_b32_e32 v4, 4, v2
	s_ashr_i32 s1, s0, 31
	v_bitop3_b32 v2, v4, v2, 32 bitop3:0x6c
	s_lshr_b32 s1, s1, 27
	v_ashrrev_i32_e32 v5, 31, v2
	s_add_i32 s1, s0, s1
	v_lshrrev_b32_e32 v5, 26, v5
	s_ashr_i32 s2, s1, 5
	v_add_u32_e32 v5, v2, v5
	s_lshl_b32 s2, s2, 3
	v_lshrrev_b32_e32 v6, 6, v5
	v_and_b32_e32 v5, 0xc0, v5
	s_sub_i32 s3, 0x84, s2
	v_lshlrev_b32_e32 v4, 3, v3
	v_lshlrev_b32_e32 v3, 5, v3
	v_sub_u32_e32 v2, v2, v5
	s_min_u32 s3, s3, 8
	s_andn2_b32 s1, s1, 31
	v_and_b32_e32 v4, 0x1ffff0, v4
	v_and_b32_e32 v3, 32, v3
	v_ashrrev_i16_sdwa v2, v163, sext(v2) dst_sel:DWORD dst_unused:UNUSED_PAD src0_sel:DWORD src1_sel:BYTE_0
	s_sub_i32 s14, s0, s1
	v_cvt_f32_ubyte0_e32 v5, s3
	v_add_u32_sdwa v2, v3, sext(v2) dst_sel:DWORD dst_unused:UNUSED_PAD src0_sel:DWORD src1_sel:WORD_0
	v_add_lshl_u32 v3, v6, v4, 11
	v_cvt_f32_i32_e32 v4, s14
	v_rcp_iflag_f32_e32 v6, v5
	v_lshl_add_u32 v138, v2, 1, v3
	s_ashr_i32 s0, s14, 30
	s_or_b32 s15, s0, 1
	v_mul_f32_e32 v2, v4, v6
	v_trunc_f32_e32 v2, v2
	v_fma_f32 v3, -v2, v5, v4
	v_cvt_i32_f32_e32 v2, v2
	v_cmp_ge_f32_e64 s[0:1], |v3|, v5
	s_and_b64 s[0:1], s[0:1], exec
	s_cselect_b32 s0, s15, 0
	v_readfirstlane_b32 s1, v2
	s_add_i32 s0, s1, s0
	s_sext_i32_i8 s1, s0
	s_mul_i32 s0, s0, s3
	s_sub_i32 s0, s14, s0
	s_sext_i32_i8 s0, s0
	s_add_i32 s2, s2, s0
	s_lshl_b32 s0, s1, 8
	s_ashr_i32 s1, s0, 31
	s_lshl_b32 s52, s2, 8
	s_lshl_b64 s[2:3], s[0:1], 11
	v_add_u32_e32 v139, s40, v136
	s_add_u32 s2, s33, s2
	v_readfirstlane_b32 s1, v139
	v_add_u32_e32 v140, 0x2000, v139
	s_addc_u32 s3, s72, s3
	v_mov_b32_e32 v2, v137
	v_mov_b32_e32 v3, v138
	s_mov_b32 m0, s1
	v_readfirstlane_b32 s1, v140
	s_ashr_i32 s53, s52, 31
	global_load_lds_dwordx4 v2, s[2:3]
	s_mov_b32 m0, s1
	v_add_u32_e32 v141, 0, v136
	global_load_lds_dwordx4 v3, s[2:3]
	s_lshl_b64 s[2:3], s[52:53], 11
	s_add_u32 s2, s42, s2
	v_readfirstlane_b32 s1, v141
	v_add_u32_e32 v142, 0x2000, v141
	s_addc_u32 s3, s43, s3
	v_mov_b32_e32 v2, v137
	v_mov_b32_e32 v3, v138
	s_mov_b32 m0, s1
	v_readfirstlane_b32 s1, v142
	v_add_u32_e32 v143, s66, v136
	global_load_lds_dwordx4 v2, s[2:3]
	s_mov_b32 m0, s1
	v_readfirstlane_b32 s1, v143
	global_load_lds_dwordx4 v3, s[2:3]
	s_or_b32 s2, s0, 0x80
	s_ashr_i32 s3, s2, 31
	s_lshl_b64 s[2:3], s[2:3], 11
	s_add_u32 s2, s33, s2
	v_add_u32_e32 v144, 0x2000, v143
	s_addc_u32 s3, s72, s3
	v_mov_b32_e32 v2, v137
	v_mov_b32_e32 v3, v138
	s_mov_b32 m0, s1
	v_readfirstlane_b32 s1, v144
	v_add_u32_e32 v145, 0x4000, v141
	global_load_lds_dwordx4 v2, s[2:3]
	s_mov_b32 m0, s1
	v_readfirstlane_b32 s1, v145
	global_load_lds_dwordx4 v3, s[2:3]
	s_or_b32 s2, s52, 0x80
	s_ashr_i32 s3, s2, 31
	s_lshl_b64 s[2:3], s[2:3], 11
	s_add_u32 s2, s42, s2
	v_add_u32_e32 v146, 0x6000, v141
	s_addc_u32 s3, s43, s3
	v_mov_b32_e32 v2, v137
	v_mov_b32_e32 v3, v138
	s_mov_b32 m0, s1
	v_readfirstlane_b32 s1, v146
	s_waitcnt lgkmcnt(0)
	v_lshlrev_b32_e32 v8, 2, v0
	global_load_lds_dwordx4 v2, s[2:3]
	s_mov_b32 m0, s1
	v_and_b32_e32 v2, 48, v0
	global_load_lds_dwordx4 v3, s[2:3]
	v_and_b32_e32 v3, 15, v0
	v_lshlrev_b32_e32 v7, 6, v3
	v_and_b32_e32 v8, 32, v8
	v_bitop3_b32 v7, v2, v8, v7 bitop3:0x36
	v_readlane_b32 s1, v254, 48
	v_bfe_u32 v4, v0, 6, 2
	v_ashrrev_i32_e32 v5, 8, v0
	v_add_u32_e32 v11, s1, v7
	v_readlane_b32 s1, v254, 49
	v_add_u32_e32 v9, s40, v7
	v_readlane_b32 s2, v255, 45
	v_add_u32_e32 v12, s1, v7
	s_movk_i32 s1, 0x100
	v_cmp_gt_u32_e64 s[40:41], s1, v0
	v_lshlrev_b32_e32 v0, 6, v0
	s_movk_i32 s1, 0x3c0
	v_and_or_b32 v0, v0, s1, v2
	v_lshlrev_b32_e32 v13, 13, v5
	v_xad_u32 v8, v0, v8, 0
	v_lshlrev_b32_e32 v0, 6, v4
	v_readlane_b32 s3, v255, 46
	v_cmp_eq_u32_e64 s[38:39], 1, v5
	v_lshlrev_b32_e32 v6, 12, v4
	v_add_u32_e32 v10, s66, v7
	v_lshl_or_b32 v147, v5, 6, v3
	v_add_u32_e32 v7, 0, v7
	v_or_b32_e32 v14, 0x800, v13
	v_or_b32_e32 v15, 0x1000, v13
	v_or_b32_e32 v16, 0x1800, v13
	v_lshl_add_u64 v[4:5], s[2:3], 0, v[0:1]
	v_mov_b32_e32 v3, v1
	v_lshl_add_u64 v[130:131], v[4:5], 0, v[2:3]
	v_add_u32_e32 v148, v9, v6
	v_add_u32_e32 v149, v7, v13
	v_add_u32_e32 v150, v8, v14
	v_add_u32_e32 v151, v8, v15
	v_add_u32_e32 v152, v8, v16
	v_add_u32_e32 v153, v10, v6
	v_add_u32_e32 v154, v11, v6
	v_add_u32_e32 v155, v12, v6
	s_branch .LBB0_298

; #define STAGE_A(P, BASE, br, kt) STAGE_B(P, BASE, br, kt)
; template <int EPI, int N, int K>
; __device__ __forceinline__ void gemm_phase(const KP& p, int l, const bfr* A, const bfr* Bt) {
;     ...
;     if (Lt + p.nblk < nwg) {
;       TILE_COORDS(Lt + p.nblk, brow, bcol, pn);
;       STAGE_B(SB(0, 0), Bt, bcol, 0); STAGE_A(SA(0, 0), A, brow, 0);
;       STAGE_B(SB(0, 1), Bt, bcol + HALF, 0); STAGE_A(SA(0, 1), A, brow + HM, 0);
;     }
.LBB0_304:
	s_or_b64 exec, exec, s[46:47]
	s_add_i32 s80, s80, s18
	s_cmpk_gt_i32 s80, 0x1ff
	s_cselect_b64 s[46:47], -1, 0
	s_and_b64 vcc, exec, s[46:47]
	s_mov_b32 s50, s52
	s_cbranch_vccnz .LBB0_297
	s_ashr_i32 s0, s80, 31
	s_lshr_b32 s0, s0, 29
	s_add_i32 s0, s80, s0
	s_ashr_i32 s1, s0, 3
	s_and_b32 s0, s0, -8
	s_sub_i32 s0, s80, s0
	s_cmp_lt_i32 s0, 0
	s_movk_i32 s2, 0x43
	s_cselect_b32 s2, s2, 0x42
	s_mul_i32 s0, s2, s0
	s_add_i32 s0, s0, s1
	s_ashr_i32 s1, s0, 31
	s_lshr_b32 s1, s1, 27
	s_add_i32 s1, s0, s1
	s_ashr_i32 s2, s1, 5
	s_lshl_b32 s2, s2, 3
	s_sub_i32 s3, 0x84, s2
	s_min_u32 s3, s3, 8
	s_andn2_b32 s1, s1, 31
	s_sub_i32 s14, s0, s1
	v_cvt_f32_ubyte0_e32 v132, s3
	v_cvt_f32_i32_e32 v0, s14
	v_rcp_iflag_f32_e32 v133, v132
	s_ashr_i32 s0, s14, 30
	s_or_b32 s15, s0, 1
	v_mul_f32_e32 v133, v0, v133
	v_trunc_f32_e32 v133, v133
	v_fma_f32 v0, -v133, v132, v0
	v_cvt_i32_f32_e32 v133, v133
	v_cmp_ge_f32_e64 s[0:1], |v0|, v132
	s_and_b64 s[0:1], s[0:1], exec
	s_cselect_b32 s0, s15, 0
	v_readfirstlane_b32 s1, v133
	s_add_i32 s0, s1, s0
	s_sext_i32_i8 s1, s0
	s_mul_i32 s0, s0, s3
	s_sub_i32 s0, s14, s0
	s_sext_i32_i8 s0, s0
	s_add_i32 s2, s2, s0
	s_lshl_b32 s0, s1, 8
	s_ashr_i32 s1, s0, 31
	s_lshl_b32 s50, s2, 8
	s_lshl_b64 s[2:3], s[0:1], 11
	s_add_u32 s2, s33, s2
	v_readfirstlane_b32 s1, v139
	s_addc_u32 s3, s72, s3
	v_mov_b32_e32 v0, v138
	v_mov_b32_e32 v132, v137
	s_mov_b32 m0, s1
	v_readfirstlane_b32 s1, v140
	s_ashr_i32 s51, s50, 31
	global_load_lds_dwordx4 v132, s[2:3]
	s_mov_b32 m0, s1
	v_readfirstlane_b32 s1, v141
	global_load_lds_dwordx4 v0, s[2:3]
	s_lshl_b64 s[2:3], s[50:51], 11
	s_add_u32 s2, s42, s2
	s_addc_u32 s3, s43, s3
	v_mov_b32_e32 v0, v137
	v_mov_b32_e32 v132, v138
	s_mov_b32 m0, s1
	v_readfirstlane_b32 s1, v142
	s_nop 0
	global_load_lds_dwordx4 v0, s[2:3]
	s_mov_b32 m0, s1
	v_readfirstlane_b32 s1, v143
	global_load_lds_dwordx4 v132, s[2:3]
	s_or_b32 s2, s0, 0x80
	s_ashr_i32 s3, s2, 31
	s_lshl_b64 s[2:3], s[2:3], 11
	s_add_u32 s2, s33, s2
	s_addc_u32 s3, s72, s3
	v_mov_b32_e32 v0, v138
	v_mov_b32_e32 v132, v137
	s_mov_b32 m0, s1
	v_readfirstlane_b32 s1, v144
	s_nop 0
	global_load_lds_dwordx4 v132, s[2:3]
	s_mov_b32 m0, s1
	v_readfirstlane_b32 s1, v145
	global_load_lds_dwordx4 v0, s[2:3]
	s_or_b32 s2, s50, 0x80
	s_ashr_i32 s3, s2, 31
	s_lshl_b64 s[2:3], s[2:3], 11
	s_add_u32 s2, s42, s2
	s_addc_u32 s3, s43, s3
	v_mov_b32_e32 v0, v138
	v_mov_b32_e32 v132, v137
	s_mov_b32 m0, s1
	v_readfirstlane_b32 s1, v146
	s_nop 0
	global_load_lds_dwordx4 v132, s[2:3]
	s_mov_b32 m0, s1
	s_nop 0
	global_load_lds_dwordx4 v0, s[2:3]
	s_branch .LBB0_297

; #define STAGE_A(P, BASE, br, kt) STAGE_B(P, BASE, br, kt)
; template <int EPI, int N, int K>
; __device__ __forceinline__ void gemm_phase(const KP& p, int l, const bfr* A, const bfr* Bt) {
;     ...
;   if (p.bid < nwg) {
;     TILE_COORDS(p.bid, brow, bcol, pn);
;     STAGE_B(SB(0, 0), Bt, bcol, 0); STAGE_A(SA(0, 0), A, brow, 0);
;     STAGE_B(SB(0, 1), Bt, bcol + HALF, 0); STAGE_A(SA(0, 1), A, brow + HM, 0);
;   }
.LBB0_1110:
	s_cmp_gt_i32 s61, 0
	s_mov_b64 s[0:1], -1
	s_cbranch_scc0 .LBB0_1123
	v_writelane_b32 v255, s0, 62
	s_mov_b32 s16, s61
	s_cmp_eq_u32 s61, 1
	v_writelane_b32 v255, s1, 63
	s_cbranch_scc0 .LBB0_1166
	v_readlane_b32 s0, v255, 42
	v_mov_b32_e32 v0, v156
	s_cmpk_gt_i32 s0, 0x1ff
	v_readlane_b32 s40, v255, 41
	s_cbranch_scc1 .LBB0_1167
	s_waitcnt vmcnt(0)
	v_bfe_i32 v3, v0, 27, 1
	v_lshlrev_b32_e32 v136, 4, v0
	v_lshrrev_b32_e32 v3, 22, v3
	v_add_u32_e32 v3, v136, v3
	v_and_b32_e32 v3, 0xfffffc00, v3
	v_sub_u32_e32 v3, v136, v3
	v_ashrrev_i32_e32 v2, 31, v0
	v_lshrrev_b32_e32 v4, 4, v3
	v_lshrrev_b32_e32 v2, 26, v2
	v_bitop3_b32 v3, v4, v3, 32 bitop3:0x6c
	v_add_u32_e32 v2, v0, v2
	v_ashrrev_i32_e32 v5, 31, v3
	v_ashrrev_i32_e32 v2, 6, v2
	v_lshrrev_b32_e32 v5, 26, v5
	v_readlane_b32 s0, v255, 57
	v_lshlrev_b32_e32 v4, 3, v2
	v_add_u32_e32 v5, v3, v5
	s_add_u32 s33, s0, 0xb00000
	v_readlane_b32 s0, v255, 58
	v_and_b32_e32 v4, 0xfffff0, v4
	v_lshrrev_b32_e32 v6, 6, v5
	v_and_b32_e32 v5, 0xc0, v5
	s_addc_u32 s50, s0, 0
	v_add_u32_e32 v4, v6, v4
	v_sub_u32_e32 v3, v3, v5
	s_movk_i32 s0, 0xb00
	v_lshlrev_b32_e32 v2, 5, v2
	v_ashrrev_i16_sdwa v3, v163, sext(v3) dst_sel:DWORD dst_unused:UNUSED_PAD src0_sel:DWORD src1_sel:BYTE_0
	v_mul_lo_u32 v4, v4, s0
	v_bfe_i32 v3, v3, 0, 16
	v_and_or_b32 v2, v2, 32, v4
	v_add_lshl_u32 v137, v2, v3, 1
	v_add_u32_e32 v2, 0x2000, v136
	v_ashrrev_i32_e32 v3, 31, v2
	v_lshrrev_b32_e32 v3, 22, v3
	v_add_u32_e32 v3, v2, v3
	v_ashrrev_i32_e32 v3, 10, v3
	v_mul_i32_i24_e32 v4, 0x400, v3
	v_sub_u32_e32 v2, v2, v4
	v_lshrrev_b32_e32 v4, 4, v2
	v_bitop3_b32 v2, v4, v2, 32 bitop3:0x6c
	v_ashrrev_i32_e32 v5, 31, v2
	v_lshrrev_b32_e32 v5, 26, v5
	v_lshlrev_b32_e32 v4, 3, v3
	v_add_u32_e32 v5, v2, v5
	v_and_b32_e32 v4, 0xfffff0, v4
	v_lshrrev_b32_e32 v6, 6, v5
	v_add_u32_e32 v4, v6, v4
	v_readlane_b32 s52, v255, 42
	v_mul_lo_u32 v4, v4, s0
	s_ashr_i32 s0, s52, 31
	s_lshr_b32 s0, s0, 29
	s_add_i32 s0, s52, s0
	s_ashr_i32 s1, s0, 3
	s_and_b32 s0, s0, -8
	s_sub_i32 s0, s52, s0
	s_cmp_lt_i32 s0, 0
	s_movk_i32 s2, 0x43
	s_cselect_b32 s2, s2, 0x42
	s_mul_i32 s0, s2, s0
	s_add_i32 s0, s0, s1
	s_ashr_i32 s1, s0, 31
	s_lshr_b32 s1, s1, 27
	s_add_i32 s1, s0, s1
	s_ashr_i32 s2, s1, 5
	s_lshl_b32 s2, s2, 3
	s_sub_i32 s3, 0x84, s2
	v_and_b32_e32 v5, 0xc0, v5
	s_min_u32 s3, s3, 8
	s_andn2_b32 s1, s1, 31
	v_lshlrev_b32_e32 v3, 5, v3
	v_sub_u32_e32 v2, v2, v5
	s_sub_i32 s14, s0, s1
	v_cvt_f32_ubyte0_e32 v5, s3
	v_and_or_b32 v3, v3, 32, v4
	v_cvt_f32_i32_e32 v4, s14
	v_rcp_iflag_f32_e32 v6, v5
	v_ashrrev_i16_sdwa v2, v163, sext(v2) dst_sel:DWORD dst_unused:UNUSED_PAD src0_sel:DWORD src1_sel:BYTE_0
	v_bfe_i32 v2, v2, 0, 16
	v_add_lshl_u32 v138, v3, v2, 1
	v_mul_f32_e32 v2, v4, v6
	v_trunc_f32_e32 v2, v2
	v_fma_f32 v3, -v2, v5, v4
	v_cvt_i32_f32_e32 v2, v2
	s_ashr_i32 s0, s14, 30
	s_or_b32 s15, s0, 1
	v_cmp_ge_f32_e64 s[0:1], |v3|, v5
	s_and_b64 s[0:1], s[0:1], exec
	s_cselect_b32 s0, s15, 0
	v_readfirstlane_b32 s1, v2
	s_add_i32 s0, s1, s0
	s_sext_i32_i8 s1, s0
	s_mul_i32 s0, s0, s3
	s_sub_i32 s0, s14, s0
	s_sext_i32_i8 s0, s0
	s_add_i32 s3, s2, s0
	s_lshl_b32 s51, s1, 8
	s_mul_i32 s1, s1, 0x160000
	s_lshl_b32 s2, s3, 8
	s_ashr_i32 s14, s1, 31
	s_add_u32 s0, s33, s1
	v_add_u32_e32 v139, s40, v136
	s_addc_u32 s1, s50, s14
	v_readfirstlane_b32 s14, v139
	v_add_u32_e32 v140, 0x2000, v139
	v_mov_b32_e32 v2, v138
	v_mov_b32_e32 v3, v137
	s_mov_b32 m0, s14
	v_readfirstlane_b32 s14, v140
	s_mul_i32 s3, s3, 0x160000
	v_add_u32_e32 v141, 0, v136
	s_mul_hi_i32 s15, s2, 0x1600
	global_load_lds_dwordx4 v3, s[0:1]
	s_mov_b32 m0, s14
	s_add_u32 s14, s36, s3
	v_readfirstlane_b32 s3, v141
	v_add_u32_e32 v142, 0x2000, v141
	global_load_lds_dwordx4 v2, s[0:1]
	s_addc_u32 s15, s37, s15
	v_mov_b32_e32 v2, v138
	v_mov_b32_e32 v3, v137
	s_mov_b32 m0, s3
	v_readfirstlane_b32 s3, v142
	v_add_u32_e32 v143, s66, v136
	s_add_u32 s0, s0, 0xb0000
	global_load_lds_dwordx4 v3, s[14:15]
	s_mov_b32 m0, s3
	v_readfirstlane_b32 s3, v143
	v_add_u32_e32 v144, 0x2000, v143
	global_load_lds_dwordx4 v2, s[14:15]
	s_addc_u32 s1, s1, 0
	v_mov_b32_e32 v2, v138
	v_mov_b32_e32 v3, v137
	s_mov_b32 m0, s3
	v_readfirstlane_b32 s3, v144
	v_add_u32_e32 v145, 0x4000, v141
	global_load_lds_dwordx4 v3, s[0:1]
	s_mov_b32 m0, s3
	v_readfirstlane_b32 s3, v145
	global_load_lds_dwordx4 v2, s[0:1]
	s_or_b32 s0, s2, 0x80
	s_mul_hi_i32 s1, s0, 0x1600
	s_mulk_i32 s0, 0x1600
	s_add_u32 s0, s36, s0
	v_add_u32_e32 v146, 0x6000, v141
	s_addc_u32 s1, s37, s1
	v_mov_b32_e32 v2, v138
	v_mov_b32_e32 v3, v137
	s_mov_b32 m0, s3
	v_readfirstlane_b32 s3, v146
	s_waitcnt lgkmcnt(0)
	v_lshlrev_b32_e32 v8, 2, v0
	global_load_lds_dwordx4 v3, s[0:1]
	s_mov_b32 m0, s3
	v_and_b32_e32 v3, 15, v0
	global_load_lds_dwordx4 v2, s[0:1]
	v_and_b32_e32 v2, 48, v0
	v_lshlrev_b32_e32 v7, 6, v3
	v_and_b32_e32 v8, 32, v8
	v_bitop3_b32 v7, v2, v8, v7 bitop3:0x36
	v_readlane_b32 s0, v254, 48
	v_bfe_u32 v4, v0, 6, 2
	v_ashrrev_i32_e32 v5, 8, v0
	v_add_u32_e32 v11, s0, v7
	v_readlane_b32 s0, v254, 49
	v_add_u32_e32 v9, s40, v7
	v_lshlrev_b32_e32 v13, 13, v5
	v_add_u32_e32 v12, s0, v7
	s_movk_i32 s0, 0x100
	v_cmp_gt_u32_e64 s[40:41], s0, v0
	v_lshlrev_b32_e32 v0, 6, v0
	s_movk_i32 s0, 0x3c0
	v_and_or_b32 v0, v0, s0, v2
	v_readlane_b32 s0, v255, 45
	v_xad_u32 v8, v0, v8, 0
	v_lshlrev_b32_e32 v0, 6, v4
	v_readlane_b32 s1, v255, 46
	v_cmp_eq_u32_e64 s[38:39], 1, v5
	v_lshlrev_b32_e32 v6, 12, v4
	v_add_u32_e32 v10, s66, v7
	v_lshl_or_b32 v147, v5, 6, v3
	v_add_u32_e32 v7, 0, v7
	v_or_b32_e32 v14, 0x800, v13
	v_or_b32_e32 v15, 0x1000, v13
	v_or_b32_e32 v16, 0x1800, v13
	v_lshl_add_u64 v[4:5], s[0:1], 0, v[0:1]
	v_mov_b32_e32 v3, v1
	v_lshl_add_u64 v[130:131], v[4:5], 0, v[2:3]
	v_add_u32_e32 v148, v9, v6
	v_add_u32_e32 v149, v7, v13
	v_add_u32_e32 v150, v8, v14
	v_add_u32_e32 v151, v8, v15
	v_add_u32_e32 v152, v8, v16
	v_add_u32_e32 v153, v10, v6
	v_add_u32_e32 v154, v11, v6
	v_add_u32_e32 v155, v12, v6
	s_branch .LBB0_1115

; #define STAGE_A(P, BASE, br, kt) STAGE_B(P, BASE, br, kt)
; template <int EPI, int N, int K>
; __device__ __forceinline__ void gemm_phase(const KP& p, int l, const bfr* A, const bfr* Bt) {
;     ...
;     if (Lt + p.nblk < nwg) {
;       TILE_COORDS(Lt + p.nblk, brow, bcol, pn);
;       STAGE_B(SB(0, 0), Bt, bcol, 0); STAGE_A(SA(0, 0), A, brow, 0);
;       STAGE_B(SB(0, 1), Bt, bcol + HALF, 0); STAGE_A(SA(0, 1), A, brow + HM, 0);
;     }
.LBB0_1121:
	s_or_b64 exec, exec, s[0:1]
	v_readlane_b32 s0, v255, 43
	s_add_i32 s52, s52, s0
	v_readlane_b32 s1, v255, 44
	s_cmpk_gt_i32 s52, 0x1ff
	s_cselect_b64 s[0:1], -1, 0
	s_and_b64 vcc, exec, s[0:1]
	s_mov_b32 s14, s2
	s_cbranch_vccnz .LBB0_1114
	s_ashr_i32 s3, s52, 31
	s_lshr_b32 s3, s3, 29
	s_add_i32 s3, s52, s3
	s_ashr_i32 s14, s3, 3
	s_and_b32 s3, s3, -8
	s_sub_i32 s3, s52, s3
	s_cmp_lt_i32 s3, 0
	s_movk_i32 s15, 0x43
	s_cselect_b32 s15, s15, 0x42
	s_mul_i32 s3, s15, s3
	s_add_i32 s3, s3, s14
	s_ashr_i32 s14, s3, 31
	s_lshr_b32 s14, s14, 27
	s_add_i32 s14, s3, s14
	s_ashr_i32 s15, s14, 5
	s_lshl_b32 s44, s15, 3
	s_sub_i32 s15, 0x84, s44
	s_min_u32 s45, s15, 8
	s_andn2_b32 s14, s14, 31
	s_sub_i32 s3, s3, s14
	v_cvt_f32_ubyte0_e32 v132, s45
	v_cvt_f32_i32_e32 v0, s3
	v_rcp_iflag_f32_e32 v133, v132
	s_ashr_i32 s14, s3, 30
	s_or_b32 s46, s14, 1
	v_mul_f32_e32 v133, v0, v133
	v_trunc_f32_e32 v133, v133
	v_fma_f32 v0, -v133, v132, v0
	v_cvt_i32_f32_e32 v133, v133
	v_cmp_ge_f32_e64 s[14:15], |v0|, v132
	s_and_b64 s[14:15], s[14:15], exec
	s_cselect_b32 s14, s46, 0
	v_readfirstlane_b32 s15, v133
	s_add_i32 s14, s15, s14
	s_sext_i32_i8 s15, s14
	s_mul_i32 s14, s14, s45
	s_sub_i32 s3, s3, s14
	s_sext_i32_i8 s3, s3
	s_add_i32 s3, s44, s3
	s_lshl_b32 s51, s15, 8
	s_mul_i32 s15, s15, 0x160000
	s_lshl_b32 s14, s3, 8
	s_ashr_i32 s45, s15, 31
	s_add_u32 s44, s33, s15
	v_readfirstlane_b32 s15, v139
	s_addc_u32 s45, s50, s45
	v_mov_b32_e32 v0, v138
	v_mov_b32_e32 v132, v137
	s_mov_b32 m0, s15
	v_readfirstlane_b32 s15, v140
	s_mul_i32 s3, s3, 0x160000
	s_add_u32 s46, s36, s3
	global_load_lds_dwordx4 v132, s[44:45]
	s_mov_b32 m0, s15
	s_mul_hi_i32 s15, s14, 0x1600
	v_readfirstlane_b32 s3, v141
	global_load_lds_dwordx4 v0, s[44:45]
	s_addc_u32 s47, s37, s15
	v_mov_b32_e32 v0, v138
	v_mov_b32_e32 v132, v137
	s_mov_b32 m0, s3
	v_readfirstlane_b32 s3, v142
	s_add_u32 s44, s44, 0xb0000
	global_load_lds_dwordx4 v132, s[46:47]
	s_mov_b32 m0, s3
	v_readfirstlane_b32 s3, v143
	global_load_lds_dwordx4 v0, s[46:47]
	s_addc_u32 s45, s45, 0
	v_mov_b32_e32 v0, v137
	v_mov_b32_e32 v132, v138
	s_mov_b32 m0, s3
	v_readfirstlane_b32 s3, v144
	s_nop 0
	global_load_lds_dwordx4 v0, s[44:45]
	s_mov_b32 m0, s3
	s_or_b32 s3, s14, 0x80
	s_mul_hi_i32 s15, s3, 0x1600
	s_mulk_i32 s3, 0x1600
	global_load_lds_dwordx4 v132, s[44:45]
	s_add_u32 s44, s36, s3
	v_readfirstlane_b32 s3, v145
	s_addc_u32 s45, s37, s15
	v_mov_b32_e32 v0, v138
	v_mov_b32_e32 v132, v137
	s_mov_b32 m0, s3
	v_readfirstlane_b32 s3, v146
	s_nop 0
	global_load_lds_dwordx4 v132, s[44:45]
	s_mov_b32 m0, s3
	s_nop 0
	global_load_lds_dwordx4 v0, s[44:45]
	s_branch .LBB0_1114

; #define STAGE_A(P, BASE, br, kt) STAGE_B(P, BASE, br, kt)
; template <int EPI, int N, int K>
; __device__ __forceinline__ void gemm_phase(const KP& p, int l, const bfr* A, const bfr* Bt) {
;     ...
;   if (p.bid < nwg) {
;     TILE_COORDS(p.bid, brow, bcol, pn);
;     STAGE_B(SB(0, 0), Bt, bcol, 0); STAGE_A(SA(0, 0), A, brow, 0);
;     STAGE_B(SB(0, 1), Bt, bcol + HALF, 0); STAGE_A(SA(0, 1), A, brow + HM, 0);
;   }
.LBB0_1125:
	s_nop 0
	v_readlane_b32 s0, v255, 62
	v_readlane_b32 s1, v255, 63
	s_and_b64 vcc, exec, s[0:1]
	s_cbranch_vccz .LBB0_1138
	v_readlane_b32 s0, v255, 42
	v_mov_b32_e32 v0, v156
	s_cmpk_gt_i32 s0, 0x1ff
	v_readlane_b32 s40, v255, 41
	s_cbranch_scc1 .LBB0_1137
	s_waitcnt vmcnt(0)
	v_bfe_i32 v3, v0, 27, 1
	v_lshlrev_b32_e32 v136, 4, v0
	v_lshrrev_b32_e32 v3, 22, v3
	v_add_u32_e32 v3, v136, v3
	v_and_b32_e32 v3, 0xfffffc00, v3
	v_sub_u32_e32 v3, v136, v3
	v_ashrrev_i32_e32 v2, 31, v0
	v_lshrrev_b32_e32 v4, 4, v3
	v_lshrrev_b32_e32 v2, 26, v2
	v_bitop3_b32 v3, v4, v3, 32 bitop3:0x6c
	v_add_u32_e32 v2, v0, v2
	v_ashrrev_i32_e32 v5, 31, v3
	v_ashrrev_i32_e32 v2, 6, v2
	v_lshrrev_b32_e32 v5, 26, v5
	v_readlane_b32 s0, v255, 57
	v_lshlrev_b32_e32 v4, 3, v2
	v_add_u32_e32 v5, v3, v5
	s_add_u32 s33, s0, 0x2500000
	v_readlane_b32 s0, v255, 58
	v_and_b32_e32 v4, 0xfffff0, v4
	v_lshrrev_b32_e32 v6, 6, v5
	v_and_b32_e32 v5, 0xc0, v5
	s_addc_u32 s50, s0, 0
	v_add_u32_e32 v4, v6, v4
	v_sub_u32_e32 v3, v3, v5
	s_movk_i32 s0, 0xb00
	v_lshlrev_b32_e32 v2, 5, v2
	v_ashrrev_i16_sdwa v3, v163, sext(v3) dst_sel:DWORD dst_unused:UNUSED_PAD src0_sel:DWORD src1_sel:BYTE_0
	v_mul_lo_u32 v4, v4, s0
	v_bfe_i32 v3, v3, 0, 16
	v_and_or_b32 v2, v2, 32, v4
	v_add_lshl_u32 v137, v2, v3, 1
	v_add_u32_e32 v2, 0x2000, v136
	v_ashrrev_i32_e32 v3, 31, v2
	v_lshrrev_b32_e32 v3, 22, v3
	v_add_u32_e32 v3, v2, v3
	v_ashrrev_i32_e32 v3, 10, v3
	v_mul_i32_i24_e32 v4, 0x400, v3
	v_sub_u32_e32 v2, v2, v4
	v_lshrrev_b32_e32 v4, 4, v2
	v_bitop3_b32 v2, v4, v2, 32 bitop3:0x6c
	v_ashrrev_i32_e32 v5, 31, v2
	v_lshrrev_b32_e32 v5, 26, v5
	v_lshlrev_b32_e32 v4, 3, v3
	v_add_u32_e32 v5, v2, v5
	v_and_b32_e32 v4, 0xfffff0, v4
	v_lshrrev_b32_e32 v6, 6, v5
	v_add_u32_e32 v4, v6, v4
	v_readlane_b32 s52, v255, 42
	v_mul_lo_u32 v4, v4, s0
	s_ashr_i32 s0, s52, 31
	s_lshr_b32 s0, s0, 29
	s_add_i32 s0, s52, s0
	s_ashr_i32 s1, s0, 3
	s_and_b32 s0, s0, -8
	s_sub_i32 s0, s52, s0
	s_cmp_lt_i32 s0, 0
	s_movk_i32 s2, 0x43
	s_cselect_b32 s2, s2, 0x42
	s_mul_i32 s0, s2, s0
	s_add_i32 s0, s0, s1
	s_ashr_i32 s1, s0, 31
	s_lshr_b32 s1, s1, 27
	s_add_i32 s1, s0, s1
	s_ashr_i32 s2, s1, 5
	s_lshl_b32 s2, s2, 3
	s_sub_i32 s3, 0x84, s2
	v_and_b32_e32 v5, 0xc0, v5
	s_min_u32 s3, s3, 8
	s_andn2_b32 s1, s1, 31
	v_lshlrev_b32_e32 v3, 5, v3
	v_sub_u32_e32 v2, v2, v5
	s_sub_i32 s14, s0, s1
	v_cvt_f32_ubyte0_e32 v5, s3
	v_and_or_b32 v3, v3, 32, v4
	v_cvt_f32_i32_e32 v4, s14
	v_rcp_iflag_f32_e32 v6, v5
	v_ashrrev_i16_sdwa v2, v163, sext(v2) dst_sel:DWORD dst_unused:UNUSED_PAD src0_sel:DWORD src1_sel:BYTE_0
	v_bfe_i32 v2, v2, 0, 16
	v_add_lshl_u32 v138, v3, v2, 1
	v_mul_f32_e32 v2, v4, v6
	v_trunc_f32_e32 v2, v2
	v_fma_f32 v3, -v2, v5, v4
	v_cvt_i32_f32_e32 v2, v2
	s_ashr_i32 s0, s14, 30
	s_or_b32 s15, s0, 1
	v_cmp_ge_f32_e64 s[0:1], |v3|, v5
	s_and_b64 s[0:1], s[0:1], exec
	s_cselect_b32 s0, s15, 0
	v_readfirstlane_b32 s1, v2
	s_add_i32 s0, s1, s0
	s_sext_i32_i8 s1, s0
	s_mul_i32 s0, s0, s3
	s_sub_i32 s0, s14, s0
	s_sext_i32_i8 s0, s0
	s_add_i32 s3, s2, s0
	s_lshl_b32 s51, s1, 8
	s_mul_i32 s1, s1, 0x160000
	s_lshl_b32 s2, s3, 8
	s_ashr_i32 s14, s1, 31
	s_add_u32 s0, s33, s1
	v_add_u32_e32 v139, s40, v136
	s_addc_u32 s1, s50, s14
	v_readfirstlane_b32 s14, v139
	v_add_u32_e32 v140, 0x2000, v139
	v_mov_b32_e32 v2, v137
	v_mov_b32_e32 v3, v138
	s_mov_b32 m0, s14
	v_readfirstlane_b32 s14, v140
	s_mul_i32 s3, s3, 0x160000
	v_add_u32_e32 v141, 0, v136
	s_mul_hi_i32 s15, s2, 0x1600
	global_load_lds_dwordx4 v2, s[0:1]
	s_mov_b32 m0, s14
	s_add_u32 s14, s36, s3
	v_readfirstlane_b32 s3, v141
	v_add_u32_e32 v142, 0x2000, v141
	global_load_lds_dwordx4 v3, s[0:1]
	s_addc_u32 s15, s37, s15
	v_mov_b32_e32 v2, v137
	v_mov_b32_e32 v3, v138
	s_mov_b32 m0, s3
	v_readfirstlane_b32 s3, v142
	v_add_u32_e32 v143, s66, v136
	s_add_u32 s0, s0, 0xb0000
	global_load_lds_dwordx4 v2, s[14:15]
	s_mov_b32 m0, s3
	v_readfirstlane_b32 s3, v143
	v_add_u32_e32 v144, 0x2000, v143
	global_load_lds_dwordx4 v3, s[14:15]
	s_addc_u32 s1, s1, 0
	v_mov_b32_e32 v2, v137
	v_mov_b32_e32 v3, v138
	s_mov_b32 m0, s3
	v_readfirstlane_b32 s3, v144
	v_add_u32_e32 v145, 0x4000, v141
	global_load_lds_dwordx4 v2, s[0:1]
	s_mov_b32 m0, s3
	v_readfirstlane_b32 s3, v145
	global_load_lds_dwordx4 v3, s[0:1]
	s_or_b32 s0, s2, 0x80
	s_mul_hi_i32 s1, s0, 0x1600
	s_mulk_i32 s0, 0x1600
	s_add_u32 s0, s36, s0
	v_add_u32_e32 v146, 0x6000, v141
	s_addc_u32 s1, s37, s1
	v_mov_b32_e32 v2, v137
	v_mov_b32_e32 v3, v138
	s_mov_b32 m0, s3
	v_readfirstlane_b32 s3, v146
	s_waitcnt lgkmcnt(0)
	v_lshlrev_b32_e32 v8, 2, v0
	global_load_lds_dwordx4 v2, s[0:1]
	s_mov_b32 m0, s3
	v_and_b32_e32 v2, 48, v0
	global_load_lds_dwordx4 v3, s[0:1]
	v_and_b32_e32 v3, 15, v0
	v_lshlrev_b32_e32 v7, 6, v3
	v_and_b32_e32 v8, 32, v8
	v_bitop3_b32 v7, v2, v8, v7 bitop3:0x36
	v_readlane_b32 s0, v254, 48
	v_bfe_u32 v4, v0, 6, 2
	v_ashrrev_i32_e32 v5, 8, v0
	v_add_u32_e32 v11, s0, v7
	v_readlane_b32 s0, v254, 49
	v_add_u32_e32 v9, s40, v7
	v_lshlrev_b32_e32 v13, 13, v5
	v_add_u32_e32 v12, s0, v7
	s_movk_i32 s0, 0x100
	v_cmp_gt_u32_e64 s[40:41], s0, v0
	v_lshlrev_b32_e32 v0, 6, v0
	s_movk_i32 s0, 0x3c0
	v_and_or_b32 v0, v0, s0, v2
	v_readlane_b32 s0, v255, 45
	v_xad_u32 v8, v0, v8, 0
	v_lshlrev_b32_e32 v0, 6, v4
	v_readlane_b32 s1, v255, 46
	v_cmp_eq_u32_e64 s[38:39], 1, v5
	v_lshlrev_b32_e32 v6, 12, v4
	v_add_u32_e32 v10, s66, v7
	v_lshl_or_b32 v147, v5, 6, v3
	v_add_u32_e32 v7, 0, v7
	v_or_b32_e32 v14, 0x800, v13
	v_or_b32_e32 v15, 0x1000, v13
	v_or_b32_e32 v16, 0x1800, v13
	v_lshl_add_u64 v[4:5], s[0:1], 0, v[0:1]
	v_mov_b32_e32 v3, v1
	v_lshl_add_u64 v[130:131], v[4:5], 0, v[2:3]
	v_add_u32_e32 v148, v9, v6
	v_add_u32_e32 v149, v7, v13
	v_add_u32_e32 v150, v8, v14
	v_add_u32_e32 v151, v8, v15
	v_add_u32_e32 v152, v8, v16
	v_add_u32_e32 v153, v10, v6
	v_add_u32_e32 v154, v11, v6
	v_add_u32_e32 v155, v12, v6
	s_branch .LBB0_1129

; #define STAGE_A(P, BASE, br, kt) STAGE_B(P, BASE, br, kt)
; template <int EPI, int N, int K>
; __device__ __forceinline__ void gemm_phase(const KP& p, int l, const bfr* A, const bfr* Bt) {
;     ...
;     if (Lt + p.nblk < nwg) {
;       TILE_COORDS(Lt + p.nblk, brow, bcol, pn);
;       STAGE_B(SB(0, 0), Bt, bcol, 0); STAGE_A(SA(0, 0), A, brow, 0);
;       STAGE_B(SB(0, 1), Bt, bcol + HALF, 0); STAGE_A(SA(0, 1), A, brow + HM, 0);
;     }
.LBB0_1135:
	s_or_b64 exec, exec, s[0:1]
	v_readlane_b32 s0, v255, 43
	s_add_i32 s52, s52, s0
	v_readlane_b32 s1, v255, 44
	s_cmpk_gt_i32 s52, 0x1ff
	s_cselect_b64 s[0:1], -1, 0
	s_and_b64 vcc, exec, s[0:1]
	s_mov_b32 s14, s2
	s_cbranch_vccnz .LBB0_1128
	s_ashr_i32 s3, s52, 31
	s_lshr_b32 s3, s3, 29
	s_add_i32 s3, s52, s3
	s_ashr_i32 s14, s3, 3
	s_and_b32 s3, s3, -8
	s_sub_i32 s3, s52, s3
	s_cmp_lt_i32 s3, 0
	s_movk_i32 s15, 0x43
	s_cselect_b32 s15, s15, 0x42
	s_mul_i32 s3, s15, s3
	s_add_i32 s3, s3, s14
	s_ashr_i32 s14, s3, 31
	s_lshr_b32 s14, s14, 27
	s_add_i32 s14, s3, s14
	s_ashr_i32 s15, s14, 5
	s_lshl_b32 s44, s15, 3
	s_sub_i32 s15, 0x84, s44
	s_min_u32 s45, s15, 8
	s_andn2_b32 s14, s14, 31
	s_sub_i32 s3, s3, s14
	v_cvt_f32_ubyte0_e32 v132, s45
	v_cvt_f32_i32_e32 v0, s3
	v_rcp_iflag_f32_e32 v133, v132
	s_ashr_i32 s14, s3, 30
	s_or_b32 s46, s14, 1
	v_mul_f32_e32 v133, v0, v133
	v_trunc_f32_e32 v133, v133
	v_fma_f32 v0, -v133, v132, v0
	v_cvt_i32_f32_e32 v133, v133
	v_cmp_ge_f32_e64 s[14:15], |v0|, v132
	s_and_b64 s[14:15], s[14:15], exec
	s_cselect_b32 s14, s46, 0
	v_readfirstlane_b32 s15, v133
	s_add_i32 s14, s15, s14
	s_sext_i32_i8 s15, s14
	s_mul_i32 s14, s14, s45
	s_sub_i32 s3, s3, s14
	s_sext_i32_i8 s3, s3
	s_add_i32 s3, s44, s3
	s_lshl_b32 s51, s15, 8
	s_mul_i32 s15, s15, 0x160000
	s_lshl_b32 s14, s3, 8
	s_ashr_i32 s45, s15, 31
	s_add_u32 s44, s33, s15
	v_readfirstlane_b32 s15, v139
	s_addc_u32 s45, s50, s45
	v_mov_b32_e32 v0, v137
	v_mov_b32_e32 v132, v138
	s_mov_b32 m0, s15
	v_readfirstlane_b32 s15, v140
	s_mul_i32 s3, s3, 0x160000
	s_add_u32 s46, s36, s3
	global_load_lds_dwordx4 v0, s[44:45]
	s_mov_b32 m0, s15
	s_mul_hi_i32 s15, s14, 0x1600
	v_readfirstlane_b32 s3, v141
	global_load_lds_dwordx4 v132, s[44:45]
	s_addc_u32 s47, s37, s15
	v_mov_b32_e32 v0, v138
	v_mov_b32_e32 v132, v137
	s_mov_b32 m0, s3
	v_readfirstlane_b32 s3, v142
	s_add_u32 s44, s44, 0xb0000
	global_load_lds_dwordx4 v132, s[46:47]
	s_mov_b32 m0, s3
	v_readfirstlane_b32 s3, v143
	global_load_lds_dwordx4 v0, s[46:47]
	s_addc_u32 s45, s45, 0
	v_mov_b32_e32 v0, v138
	v_mov_b32_e32 v132, v137
	s_mov_b32 m0, s3
	v_readfirstlane_b32 s3, v144
	s_nop 0
	global_load_lds_dwordx4 v132, s[44:45]
	s_mov_b32 m0, s3
	s_or_b32 s3, s14, 0x80
	s_mul_hi_i32 s15, s3, 0x1600
	s_mulk_i32 s3, 0x1600
	global_load_lds_dwordx4 v0, s[44:45]
	s_add_u32 s44, s36, s3
	v_readfirstlane_b32 s3, v145
	s_addc_u32 s45, s37, s15
	v_mov_b32_e32 v0, v137
	v_mov_b32_e32 v132, v138
	s_mov_b32 m0, s3
	v_readfirstlane_b32 s3, v146
	s_nop 0
	global_load_lds_dwordx4 v0, s[44:45]
	s_mov_b32 m0, s3
	s_nop 0
	global_load_lds_dwordx4 v132, s[44:45]
	s_branch .LBB0_1128
